# diff attention: first K fragment reads hoisted above the DMA issue block, K fragment prefetch depth 3
# speedup vs baseline: 1.0250x; 1.0013x over previous
.LBB0_788:
	ds_read_b128 v[238:241], v218 offset:0
	ds_read_b128 v[242:245], v219 offset:0
	ds_read_b128 v[246:249], v218 offset:128
	s_add_i32 s36, s57, -2
	s_cmp_ge_u32 s36, s55
	v_lshl_add_u64 v[206:207], s[34:35], 0, v[200:201]
	v_lshl_add_u64 v[204:205], s[34:35], 0, v[198:199]
	v_lshl_add_u64 v[202:203], s[34:35], 0, v[196:197]
	s_cbranch_scc1 .LBB0_790
	s_mov_b64 s[36:37], src_shared_base
	s_cmp_lg_u32 0, -1
	s_cselect_b32 s36, 0, 0
	s_cselect_b32 s37, s37, 0
	s_add_u32 s36, s36, 0x10000
	s_addc_u32 s37, s37, 0
	s_cmp_lg_u64 s[36:37], 0
	s_cselect_b32 s36, s36, -1
	s_add_i32 s36, s36, s53
	v_lshl_add_u64 v[130:131], v[206:207], 0, s[10:11]
	s_add_i32 m0, s36, 0x4000
	s_nop 0
	global_load_lds_dwordx4 v[130:131], off
	v_lshl_add_u64 v[130:131], v[204:205], 0, s[10:11]
	s_add_i32 m0, s36, 0x4400
	s_add_i32 s36, s54, 0
	global_load_lds_dwordx4 v[130:131], off
	v_lshl_add_u64 v[130:131], v[202:203], 0, s[12:13]
	s_add_i32 m0, s36, 0x8000
	s_nop 0
	global_load_lds_dwordx4 v[130:131], off
	v_lshl_add_u64 v[130:131], v[202:203], 0, s[14:15]
	s_add_i32 m0, s36, 0x8400
	s_nop 0
	global_load_lds_dwordx4 v[130:131], off
	v_lshl_add_u64 v[130:131], v[202:203], 0, s[16:17]
	s_add_i32 m0, s36, 0x8800
	s_nop 0
	global_load_lds_dwordx4 v[130:131], off
	v_lshl_add_u64 v[130:131], v[202:203], 0, s[18:19]
	s_add_i32 m0, s36, 0x8c00
	s_nop 0
	global_load_lds_dwordx4 v[130:131], off
.LBB0_790:
	s_sub_i32 s73, s56, 158
	s_cmp_gt_i32 s73, s4
	s_cbranch_scc1 .Ld16a_end0
	ds_read_b128 v[252:255], v219 offset:128
	s_waitcnt lgkmcnt(3)
	v_mfma_f32_16x16x32_bf16 v[130:133], v[238:241], v[162:165], 0
	v_mfma_f32_16x16x32_bf16 v[146:149], v[238:241], v[178:181], 0
	ds_read_b128 v[238:241], v218 offset:4096
	s_waitcnt lgkmcnt(3)
	v_mfma_f32_16x16x32_bf16 v[130:133], v[242:245], v[166:169], v[130:133]
	v_mfma_f32_16x16x32_bf16 v[146:149], v[242:245], v[182:185], v[146:149]
	ds_read_b128 v[242:245], v219 offset:4096
	s_waitcnt lgkmcnt(3)
	v_mfma_f32_16x16x32_bf16 v[130:133], v[246:249], v[170:173], v[130:133]
	v_mfma_f32_16x16x32_bf16 v[146:149], v[246:249], v[186:189], v[146:149]
	ds_read_b128 v[246:249], v218 offset:4224
	s_waitcnt lgkmcnt(3)
	v_mfma_f32_16x16x32_bf16 v[130:133], v[252:255], v[174:177], v[130:133]
	v_mfma_f32_16x16x32_bf16 v[146:149], v[252:255], v[190:193], v[146:149]
	ds_read_b128 v[252:255], v219 offset:4224
	s_waitcnt lgkmcnt(3)
	v_mfma_f32_16x16x32_bf16 v[134:137], v[238:241], v[162:165], 0
	v_mfma_f32_16x16x32_bf16 v[150:153], v[238:241], v[178:181], 0
	ds_read_b128 v[238:241], v218 offset:8192
	s_waitcnt lgkmcnt(3)
	v_mfma_f32_16x16x32_bf16 v[134:137], v[242:245], v[166:169], v[134:137]
	v_mfma_f32_16x16x32_bf16 v[150:153], v[242:245], v[182:185], v[150:153]
	ds_read_b128 v[242:245], v219 offset:8192
	s_waitcnt lgkmcnt(3)
	v_mfma_f32_16x16x32_bf16 v[134:137], v[246:249], v[170:173], v[134:137]
	v_mfma_f32_16x16x32_bf16 v[150:153], v[246:249], v[186:189], v[150:153]
	ds_read_b128 v[246:249], v218 offset:8320
	s_waitcnt lgkmcnt(3)
	v_mfma_f32_16x16x32_bf16 v[134:137], v[252:255], v[174:177], v[134:137]
	v_mfma_f32_16x16x32_bf16 v[150:153], v[252:255], v[190:193], v[150:153]
	ds_read_b128 v[252:255], v219 offset:8320
	s_waitcnt lgkmcnt(3)
	v_mfma_f32_16x16x32_bf16 v[138:141], v[238:241], v[162:165], 0
	v_mfma_f32_16x16x32_bf16 v[154:157], v[238:241], v[178:181], 0
	ds_read_b128 v[238:241], v218 offset:12288
	s_waitcnt lgkmcnt(3)
	v_mfma_f32_16x16x32_bf16 v[138:141], v[242:245], v[166:169], v[138:141]
	v_mfma_f32_16x16x32_bf16 v[154:157], v[242:245], v[182:185], v[154:157]
	ds_read_b128 v[242:245], v219 offset:12288
	s_waitcnt lgkmcnt(3)
	v_mfma_f32_16x16x32_bf16 v[138:141], v[246:249], v[170:173], v[138:141]
	v_mfma_f32_16x16x32_bf16 v[154:157], v[246:249], v[186:189], v[154:157]
	ds_read_b128 v[246:249], v218 offset:12416
	s_waitcnt lgkmcnt(3)
	v_mfma_f32_16x16x32_bf16 v[138:141], v[252:255], v[174:177], v[138:141]
	v_mfma_f32_16x16x32_bf16 v[154:157], v[252:255], v[190:193], v[154:157]
	ds_read_b128 v[252:255], v219 offset:12416
	s_waitcnt lgkmcnt(3)
	v_mfma_f32_16x16x32_bf16 v[142:145], v[238:241], v[162:165], 0
	v_mfma_f32_16x16x32_bf16 v[158:161], v[238:241], v[178:181], 0
	s_waitcnt lgkmcnt(2)
	v_mfma_f32_16x16x32_bf16 v[142:145], v[242:245], v[166:169], v[142:145]
	v_mfma_f32_16x16x32_bf16 v[158:161], v[242:245], v[182:185], v[158:161]
	s_waitcnt lgkmcnt(1)
	v_mfma_f32_16x16x32_bf16 v[142:145], v[246:249], v[170:173], v[142:145]
	v_mfma_f32_16x16x32_bf16 v[158:161], v[246:249], v[186:189], v[158:161]
	s_waitcnt lgkmcnt(0)
	v_mfma_f32_16x16x32_bf16 v[142:145], v[252:255], v[174:177], v[142:145]
	v_mfma_f32_16x16x32_bf16 v[158:161], v[252:255], v[190:193], v[158:161]
	s_nop 7
	s_nop 1
	s_sub_i32 s36, s56, 64
	s_cmp_le_i32 s36, s4
	s_cbranch_scc1 .Ld16a_nm0
	v_cmp_gt_i32_e64 s[74:75], 0, v233
	v_cmp_gt_i32_e64 s[76:77], 1, v233
	v_cmp_gt_i32_e64 s[78:79], 2, v233
	v_cmp_gt_i32_e64 s[80:81], 3, v233
	v_cndmask_b32_e64 v130, v130, v230, s[74:75]
	v_cndmask_b32_e64 v131, v131, v230, s[76:77]
	v_cndmask_b32_e64 v132, v132, v230, s[78:79]
	v_cndmask_b32_e64 v133, v133, v230, s[80:81]
	v_cmp_gt_i32_e64 s[74:75], 16, v233
	v_cmp_gt_i32_e64 s[76:77], 17, v233
	v_cmp_gt_i32_e64 s[78:79], 18, v233
	v_cmp_gt_i32_e64 s[80:81], 19, v233
	v_cndmask_b32_e64 v134, v134, v230, s[74:75]
	v_cndmask_b32_e64 v135, v135, v230, s[76:77]
	v_cndmask_b32_e64 v136, v136, v230, s[78:79]
	v_cndmask_b32_e64 v137, v137, v230, s[80:81]
	v_cmp_gt_i32_e64 s[74:75], 32, v233
	v_cmp_gt_i32_e64 s[76:77], 33, v233
	v_cmp_gt_i32_e64 s[78:79], 34, v233
	v_cmp_gt_i32_e64 s[80:81], 35, v233
	v_cndmask_b32_e64 v138, v138, v230, s[74:75]
	v_cndmask_b32_e64 v139, v139, v230, s[76:77]
	v_cndmask_b32_e64 v140, v140, v230, s[78:79]
	v_cndmask_b32_e64 v141, v141, v230, s[80:81]
	v_cmp_gt_i32_e64 s[74:75], 48, v233
	v_cmp_gt_i32_e64 s[76:77], 49, v233
	v_cmp_gt_i32_e64 s[78:79], 50, v233
	v_cmp_gt_i32_e64 s[80:81], 51, v233
	v_cndmask_b32_e64 v142, v142, v230, s[74:75]
	v_cndmask_b32_e64 v143, v143, v230, s[76:77]
	v_cndmask_b32_e64 v144, v144, v230, s[78:79]
	v_cndmask_b32_e64 v145, v145, v230, s[80:81]
	v_cmp_gt_i32_e64 s[74:75], -16, v233
	v_cmp_gt_i32_e64 s[76:77], -15, v233
	v_cmp_gt_i32_e64 s[78:79], -14, v233
	v_cmp_gt_i32_e64 s[80:81], -13, v233
	v_cndmask_b32_e64 v146, v146, v230, s[74:75]
	v_cndmask_b32_e64 v147, v147, v230, s[76:77]
	v_cndmask_b32_e64 v148, v148, v230, s[78:79]
	v_cndmask_b32_e64 v149, v149, v230, s[80:81]
	v_cmp_gt_i32_e64 s[74:75], 0, v233
	v_cmp_gt_i32_e64 s[76:77], 1, v233
	v_cmp_gt_i32_e64 s[78:79], 2, v233
	v_cmp_gt_i32_e64 s[80:81], 3, v233
	v_cndmask_b32_e64 v150, v150, v230, s[74:75]
	v_cndmask_b32_e64 v151, v151, v230, s[76:77]
	v_cndmask_b32_e64 v152, v152, v230, s[78:79]
	v_cndmask_b32_e64 v153, v153, v230, s[80:81]
	v_cmp_gt_i32_e64 s[74:75], 16, v233
	v_cmp_gt_i32_e64 s[76:77], 17, v233
	v_cmp_gt_i32_e64 s[78:79], 18, v233
	v_cmp_gt_i32_e64 s[80:81], 19, v233
	v_cndmask_b32_e64 v154, v154, v230, s[74:75]
	v_cndmask_b32_e64 v155, v155, v230, s[76:77]
	v_cndmask_b32_e64 v156, v156, v230, s[78:79]
	v_cndmask_b32_e64 v157, v157, v230, s[80:81]
	v_cmp_gt_i32_e64 s[74:75], 32, v233
	v_cmp_gt_i32_e64 s[76:77], 33, v233
	v_cmp_gt_i32_e64 s[78:79], 34, v233
	v_cmp_gt_i32_e64 s[80:81], 35, v233
	v_cndmask_b32_e64 v158, v158, v230, s[74:75]
	v_cndmask_b32_e64 v159, v159, v230, s[76:77]
	v_cndmask_b32_e64 v160, v160, v230, s[78:79]
	v_cndmask_b32_e64 v161, v161, v230, s[80:81]

.Ld16a_end0:
	s_waitcnt vmcnt(0)
	s_cmp_gt_u32 s57, s55
	s_cselect_b64 s[36:37], -1, 0
	s_and_b64 vcc, exec, s[36:37]
	s_waitcnt vmcnt(0) lgkmcnt(0)
	s_barrier
	ds_read_b128 v[238:241], v218 offset:16384
	ds_read_b128 v[242:245], v219 offset:16384
	ds_read_b128 v[246:249], v218 offset:16512
	s_cbranch_vccnz .LBB0_798
	s_mov_b64 s[38:39], src_shared_base
	s_cmp_lg_u32 0, -1
	s_cselect_b32 s38, 0, 0
	s_cselect_b32 s39, s39, 0
	s_add_u32 s38, s38, 0x10000
	s_addc_u32 s39, s39, 0
	s_cmp_lg_u64 s[38:39], 0
	s_cselect_b32 s38, s38, -1
	s_add_i32 s38, s38, s53
	v_lshl_add_u64 v[130:131], v[206:207], 0, s[20:21]
	s_mov_b32 m0, s38
	s_nop 0
	global_load_lds_dwordx4 v[130:131], off
	v_lshl_add_u64 v[130:131], v[204:205], 0, s[20:21]
	s_add_i32 m0, s38, 0x400
	s_add_i32 s38, s54, 0
	global_load_lds_dwordx4 v[130:131], off
	v_lshl_add_u64 v[130:131], v[202:203], 0, s[22:23]
	s_mov_b32 m0, s38
	s_nop 0
	global_load_lds_dwordx4 v[130:131], off
	v_lshl_add_u64 v[130:131], v[202:203], 0, s[24:25]
	s_add_i32 m0, s38, 0x400
	s_nop 0
	global_load_lds_dwordx4 v[130:131], off
	v_lshl_add_u64 v[130:131], v[202:203], 0, s[26:27]
	s_add_i32 m0, s38, 0x800
	s_nop 0
	global_load_lds_dwordx4 v[130:131], off
	v_lshl_add_u64 v[130:131], v[202:203], 0, s[28:29]
	s_add_i32 m0, s38, 0xc00
	s_nop 0
	global_load_lds_dwordx4 v[130:131], off
.LBB0_798:
	s_sub_i32 s73, s56, 94
	s_cmp_gt_i32 s73, s4
	s_cbranch_scc1 .Ld16a_end1
	ds_read_b128 v[252:255], v219 offset:16512
	s_waitcnt lgkmcnt(3)
	v_mfma_f32_16x16x32_bf16 v[130:133], v[238:241], v[162:165], 0
	v_mfma_f32_16x16x32_bf16 v[146:149], v[238:241], v[178:181], 0
	ds_read_b128 v[238:241], v218 offset:20480
	s_waitcnt lgkmcnt(3)
	v_mfma_f32_16x16x32_bf16 v[130:133], v[242:245], v[166:169], v[130:133]
	v_mfma_f32_16x16x32_bf16 v[146:149], v[242:245], v[182:185], v[146:149]
	ds_read_b128 v[242:245], v219 offset:20480
	s_waitcnt lgkmcnt(3)
	v_mfma_f32_16x16x32_bf16 v[130:133], v[246:249], v[170:173], v[130:133]
	v_mfma_f32_16x16x32_bf16 v[146:149], v[246:249], v[186:189], v[146:149]
	ds_read_b128 v[246:249], v218 offset:20608
	s_waitcnt lgkmcnt(3)
	v_mfma_f32_16x16x32_bf16 v[130:133], v[252:255], v[174:177], v[130:133]
	v_mfma_f32_16x16x32_bf16 v[146:149], v[252:255], v[190:193], v[146:149]
	ds_read_b128 v[252:255], v219 offset:20608
	s_waitcnt lgkmcnt(3)
	v_mfma_f32_16x16x32_bf16 v[134:137], v[238:241], v[162:165], 0
	v_mfma_f32_16x16x32_bf16 v[150:153], v[238:241], v[178:181], 0
	ds_read_b128 v[238:241], v218 offset:24576
	s_waitcnt lgkmcnt(3)
	v_mfma_f32_16x16x32_bf16 v[134:137], v[242:245], v[166:169], v[134:137]
	v_mfma_f32_16x16x32_bf16 v[150:153], v[242:245], v[182:185], v[150:153]
	ds_read_b128 v[242:245], v219 offset:24576
	s_waitcnt lgkmcnt(3)
	v_mfma_f32_16x16x32_bf16 v[134:137], v[246:249], v[170:173], v[134:137]
	v_mfma_f32_16x16x32_bf16 v[150:153], v[246:249], v[186:189], v[150:153]
	ds_read_b128 v[246:249], v218 offset:24704
	s_waitcnt lgkmcnt(3)
	v_mfma_f32_16x16x32_bf16 v[134:137], v[252:255], v[174:177], v[134:137]
	v_mfma_f32_16x16x32_bf16 v[150:153], v[252:255], v[190:193], v[150:153]
	ds_read_b128 v[252:255], v219 offset:24704
	s_waitcnt lgkmcnt(3)
	v_mfma_f32_16x16x32_bf16 v[138:141], v[238:241], v[162:165], 0
	v_mfma_f32_16x16x32_bf16 v[154:157], v[238:241], v[178:181], 0
	ds_read_b128 v[238:241], v218 offset:28672
	s_waitcnt lgkmcnt(3)
	v_mfma_f32_16x16x32_bf16 v[138:141], v[242:245], v[166:169], v[138:141]
	v_mfma_f32_16x16x32_bf16 v[154:157], v[242:245], v[182:185], v[154:157]
	ds_read_b128 v[242:245], v219 offset:28672
	s_waitcnt lgkmcnt(3)
	v_mfma_f32_16x16x32_bf16 v[138:141], v[246:249], v[170:173], v[138:141]
	v_mfma_f32_16x16x32_bf16 v[154:157], v[246:249], v[186:189], v[154:157]
	ds_read_b128 v[246:249], v218 offset:28800
	s_waitcnt lgkmcnt(3)
	v_mfma_f32_16x16x32_bf16 v[138:141], v[252:255], v[174:177], v[138:141]
	v_mfma_f32_16x16x32_bf16 v[154:157], v[252:255], v[190:193], v[154:157]
	ds_read_b128 v[252:255], v219 offset:28800
	s_waitcnt lgkmcnt(3)
	v_mfma_f32_16x16x32_bf16 v[142:145], v[238:241], v[162:165], 0
	v_mfma_f32_16x16x32_bf16 v[158:161], v[238:241], v[178:181], 0
	s_waitcnt lgkmcnt(2)
	v_mfma_f32_16x16x32_bf16 v[142:145], v[242:245], v[166:169], v[142:145]
	v_mfma_f32_16x16x32_bf16 v[158:161], v[242:245], v[182:185], v[158:161]
	s_waitcnt lgkmcnt(1)
	v_mfma_f32_16x16x32_bf16 v[142:145], v[246:249], v[170:173], v[142:145]
	v_mfma_f32_16x16x32_bf16 v[158:161], v[246:249], v[186:189], v[158:161]
	s_waitcnt lgkmcnt(0)
	v_mfma_f32_16x16x32_bf16 v[142:145], v[252:255], v[174:177], v[142:145]
	v_mfma_f32_16x16x32_bf16 v[158:161], v[252:255], v[190:193], v[158:161]
	s_nop 7
	s_nop 1
	s_cmp_le_i32 s56, s4
	s_cbranch_scc1 .Ld16a_nm1
	v_subrev_u32_e32 v246, 64, v233
	v_cmp_gt_i32_e64 s[74:75], 0, v246
	v_cmp_gt_i32_e64 s[76:77], 1, v246
	v_cmp_gt_i32_e64 s[78:79], 2, v246
	v_cmp_gt_i32_e64 s[80:81], 3, v246
	v_cndmask_b32_e64 v130, v130, v230, s[74:75]
	v_cndmask_b32_e64 v131, v131, v230, s[76:77]
	v_cndmask_b32_e64 v132, v132, v230, s[78:79]
	v_cndmask_b32_e64 v133, v133, v230, s[80:81]
	v_cmp_gt_i32_e64 s[74:75], 16, v246
	v_cmp_gt_i32_e64 s[76:77], 17, v246
	v_cmp_gt_i32_e64 s[78:79], 18, v246
	v_cmp_gt_i32_e64 s[80:81], 19, v246
	v_cndmask_b32_e64 v134, v134, v230, s[74:75]
	v_cndmask_b32_e64 v135, v135, v230, s[76:77]
	v_cndmask_b32_e64 v136, v136, v230, s[78:79]
	v_cndmask_b32_e64 v137, v137, v230, s[80:81]
	v_cmp_gt_i32_e64 s[74:75], 32, v246
	v_cmp_gt_i32_e64 s[76:77], 33, v246
	v_cmp_gt_i32_e64 s[78:79], 34, v246
	v_cmp_gt_i32_e64 s[80:81], 35, v246
	v_cndmask_b32_e64 v138, v138, v230, s[74:75]
	v_cndmask_b32_e64 v139, v139, v230, s[76:77]
	v_cndmask_b32_e64 v140, v140, v230, s[78:79]
	v_cndmask_b32_e64 v141, v141, v230, s[80:81]
	v_cmp_gt_i32_e64 s[74:75], 48, v246
	v_cmp_gt_i32_e64 s[76:77], 49, v246
	v_cmp_gt_i32_e64 s[78:79], 50, v246
	v_cmp_gt_i32_e64 s[80:81], 51, v246
	v_cndmask_b32_e64 v142, v142, v230, s[74:75]
	v_cndmask_b32_e64 v143, v143, v230, s[76:77]
	v_cndmask_b32_e64 v144, v144, v230, s[78:79]
	v_cndmask_b32_e64 v145, v145, v230, s[80:81]
	v_cmp_gt_i32_e64 s[74:75], -16, v246
	v_cmp_gt_i32_e64 s[76:77], -15, v246
	v_cmp_gt_i32_e64 s[78:79], -14, v246
	v_cmp_gt_i32_e64 s[80:81], -13, v246
	v_cndmask_b32_e64 v146, v146, v230, s[74:75]
	v_cndmask_b32_e64 v147, v147, v230, s[76:77]
	v_cndmask_b32_e64 v148, v148, v230, s[78:79]
	v_cndmask_b32_e64 v149, v149, v230, s[80:81]
	v_cmp_gt_i32_e64 s[74:75], 0, v246
	v_cmp_gt_i32_e64 s[76:77], 1, v246
	v_cmp_gt_i32_e64 s[78:79], 2, v246
	v_cmp_gt_i32_e64 s[80:81], 3, v246
	v_cndmask_b32_e64 v150, v150, v230, s[74:75]
	v_cndmask_b32_e64 v151, v151, v230, s[76:77]
	v_cndmask_b32_e64 v152, v152, v230, s[78:79]
	v_cndmask_b32_e64 v153, v153, v230, s[80:81]
	v_cmp_gt_i32_e64 s[74:75], 16, v246
	v_cmp_gt_i32_e64 s[76:77], 17, v246
	v_cmp_gt_i32_e64 s[78:79], 18, v246
	v_cmp_gt_i32_e64 s[80:81], 19, v246
	v_cndmask_b32_e64 v154, v154, v230, s[74:75]
	v_cndmask_b32_e64 v155, v155, v230, s[76:77]
	v_cndmask_b32_e64 v156, v156, v230, s[78:79]
	v_cndmask_b32_e64 v157, v157, v230, s[80:81]
	v_cmp_gt_i32_e64 s[74:75], 32, v246
	v_cmp_gt_i32_e64 s[76:77], 33, v246
	v_cmp_gt_i32_e64 s[78:79], 34, v246
	v_cmp_gt_i32_e64 s[80:81], 35, v246
	v_cndmask_b32_e64 v158, v158, v230, s[74:75]
	v_cndmask_b32_e64 v159, v159, v230, s[76:77]
	v_cndmask_b32_e64 v160, v160, v230, s[78:79]
	v_cndmask_b32_e64 v161, v161, v230, s[80:81]

.LBB0_2408:
	ds_read_b128 v[238:241], v218 offset:0
	ds_read_b128 v[242:245], v219 offset:0
	ds_read_b128 v[246:249], v218 offset:128
	s_add_i32 s40, s61, -2
	s_cmp_ge_u32 s40, s59
	v_lshl_add_u64 v[206:207], s[38:39], 0, v[200:201]
	v_lshl_add_u64 v[204:205], s[38:39], 0, v[198:199]
	v_lshl_add_u64 v[202:203], s[38:39], 0, v[196:197]
	s_cbranch_scc1 .LBB0_2410
	s_mov_b64 s[40:41], src_shared_base
	s_cmp_lg_u32 0, -1
	s_cselect_b32 s40, 0, 0
	s_cselect_b32 s41, s41, 0
	s_add_u32 s40, s40, 0x10000
	s_addc_u32 s41, s41, 0
	s_cmp_lg_u64 s[40:41], 0
	s_cselect_b32 s40, s40, -1
	s_add_i32 s40, s40, s57
	v_lshl_add_u64 v[130:131], v[206:207], 0, s[14:15]
	s_add_i32 m0, s40, 0x4000
	s_nop 0
	global_load_lds_dwordx4 v[130:131], off
	v_lshl_add_u64 v[130:131], v[204:205], 0, s[14:15]
	s_add_i32 m0, s40, 0x4400
	s_add_i32 s40, s58, 0
	global_load_lds_dwordx4 v[130:131], off
	v_lshl_add_u64 v[130:131], v[202:203], 0, s[16:17]
	s_add_i32 m0, s40, 0x8000
	s_nop 0
	global_load_lds_dwordx4 v[130:131], off
	v_lshl_add_u64 v[130:131], v[202:203], 0, s[18:19]
	s_add_i32 m0, s40, 0x8400
	s_nop 0
	global_load_lds_dwordx4 v[130:131], off
	v_lshl_add_u64 v[130:131], v[202:203], 0, s[20:21]
	s_add_i32 m0, s40, 0x8800
	s_nop 0
	global_load_lds_dwordx4 v[130:131], off
	v_lshl_add_u64 v[130:131], v[202:203], 0, s[22:23]
	s_add_i32 m0, s40, 0x8c00
	s_nop 0
	global_load_lds_dwordx4 v[130:131], off
.LBB0_2410:
	s_sub_i32 s73, s60, 158
	s_cmp_gt_i32 s73, s4
	s_cbranch_scc1 .Ld16c_end0
	ds_read_b128 v[252:255], v219 offset:128
	s_waitcnt lgkmcnt(3)
	v_mfma_f32_16x16x32_bf16 v[130:133], v[238:241], v[162:165], 0
	v_mfma_f32_16x16x32_bf16 v[146:149], v[238:241], v[178:181], 0
	ds_read_b128 v[238:241], v218 offset:4096
	s_waitcnt lgkmcnt(3)
	v_mfma_f32_16x16x32_bf16 v[130:133], v[242:245], v[166:169], v[130:133]
	v_mfma_f32_16x16x32_bf16 v[146:149], v[242:245], v[182:185], v[146:149]
	ds_read_b128 v[242:245], v219 offset:4096
	s_waitcnt lgkmcnt(3)
	v_mfma_f32_16x16x32_bf16 v[130:133], v[246:249], v[170:173], v[130:133]
	v_mfma_f32_16x16x32_bf16 v[146:149], v[246:249], v[186:189], v[146:149]
	ds_read_b128 v[246:249], v218 offset:4224
	s_waitcnt lgkmcnt(3)
	v_mfma_f32_16x16x32_bf16 v[130:133], v[252:255], v[174:177], v[130:133]
	v_mfma_f32_16x16x32_bf16 v[146:149], v[252:255], v[190:193], v[146:149]
	ds_read_b128 v[252:255], v219 offset:4224
	s_waitcnt lgkmcnt(3)
	v_mfma_f32_16x16x32_bf16 v[134:137], v[238:241], v[162:165], 0
	v_mfma_f32_16x16x32_bf16 v[150:153], v[238:241], v[178:181], 0
	ds_read_b128 v[238:241], v218 offset:8192
	s_waitcnt lgkmcnt(3)
	v_mfma_f32_16x16x32_bf16 v[134:137], v[242:245], v[166:169], v[134:137]
	v_mfma_f32_16x16x32_bf16 v[150:153], v[242:245], v[182:185], v[150:153]
	ds_read_b128 v[242:245], v219 offset:8192
	s_waitcnt lgkmcnt(3)
	v_mfma_f32_16x16x32_bf16 v[134:137], v[246:249], v[170:173], v[134:137]
	v_mfma_f32_16x16x32_bf16 v[150:153], v[246:249], v[186:189], v[150:153]
	ds_read_b128 v[246:249], v218 offset:8320
	s_waitcnt lgkmcnt(3)
	v_mfma_f32_16x16x32_bf16 v[134:137], v[252:255], v[174:177], v[134:137]
	v_mfma_f32_16x16x32_bf16 v[150:153], v[252:255], v[190:193], v[150:153]
	ds_read_b128 v[252:255], v219 offset:8320
	s_waitcnt lgkmcnt(3)
	v_mfma_f32_16x16x32_bf16 v[138:141], v[238:241], v[162:165], 0
	v_mfma_f32_16x16x32_bf16 v[154:157], v[238:241], v[178:181], 0
	ds_read_b128 v[238:241], v218 offset:12288
	s_waitcnt lgkmcnt(3)
	v_mfma_f32_16x16x32_bf16 v[138:141], v[242:245], v[166:169], v[138:141]
	v_mfma_f32_16x16x32_bf16 v[154:157], v[242:245], v[182:185], v[154:157]
	ds_read_b128 v[242:245], v219 offset:12288
	s_waitcnt lgkmcnt(3)
	v_mfma_f32_16x16x32_bf16 v[138:141], v[246:249], v[170:173], v[138:141]
	v_mfma_f32_16x16x32_bf16 v[154:157], v[246:249], v[186:189], v[154:157]
	ds_read_b128 v[246:249], v218 offset:12416
	s_waitcnt lgkmcnt(3)
	v_mfma_f32_16x16x32_bf16 v[138:141], v[252:255], v[174:177], v[138:141]
	v_mfma_f32_16x16x32_bf16 v[154:157], v[252:255], v[190:193], v[154:157]
	ds_read_b128 v[252:255], v219 offset:12416
	s_waitcnt lgkmcnt(3)
	v_mfma_f32_16x16x32_bf16 v[142:145], v[238:241], v[162:165], 0
	v_mfma_f32_16x16x32_bf16 v[158:161], v[238:241], v[178:181], 0
	s_waitcnt lgkmcnt(2)
	v_mfma_f32_16x16x32_bf16 v[142:145], v[242:245], v[166:169], v[142:145]
	v_mfma_f32_16x16x32_bf16 v[158:161], v[242:245], v[182:185], v[158:161]
	s_waitcnt lgkmcnt(1)
	v_mfma_f32_16x16x32_bf16 v[142:145], v[246:249], v[170:173], v[142:145]
	v_mfma_f32_16x16x32_bf16 v[158:161], v[246:249], v[186:189], v[158:161]
	s_waitcnt lgkmcnt(0)
	v_mfma_f32_16x16x32_bf16 v[142:145], v[252:255], v[174:177], v[142:145]
	v_mfma_f32_16x16x32_bf16 v[158:161], v[252:255], v[190:193], v[158:161]
	s_nop 7
	s_nop 1
	s_sub_i32 s40, s60, 64
	s_cmp_le_i32 s40, s4
	s_cbranch_scc1 .Ld16c_nm0
	v_cmp_gt_i32_e64 s[74:75], 0, v233
	v_cmp_gt_i32_e64 s[76:77], 1, v233
	v_cmp_gt_i32_e64 s[78:79], 2, v233
	v_cmp_gt_i32_e64 s[80:81], 3, v233
	v_cndmask_b32_e64 v130, v130, v230, s[74:75]
	v_cndmask_b32_e64 v131, v131, v230, s[76:77]
	v_cndmask_b32_e64 v132, v132, v230, s[78:79]
	v_cndmask_b32_e64 v133, v133, v230, s[80:81]
	v_cmp_gt_i32_e64 s[74:75], 16, v233
	v_cmp_gt_i32_e64 s[76:77], 17, v233
	v_cmp_gt_i32_e64 s[78:79], 18, v233
	v_cmp_gt_i32_e64 s[80:81], 19, v233
	v_cndmask_b32_e64 v134, v134, v230, s[74:75]
	v_cndmask_b32_e64 v135, v135, v230, s[76:77]
	v_cndmask_b32_e64 v136, v136, v230, s[78:79]
	v_cndmask_b32_e64 v137, v137, v230, s[80:81]
	v_cmp_gt_i32_e64 s[74:75], 32, v233
	v_cmp_gt_i32_e64 s[76:77], 33, v233
	v_cmp_gt_i32_e64 s[78:79], 34, v233
	v_cmp_gt_i32_e64 s[80:81], 35, v233
	v_cndmask_b32_e64 v138, v138, v230, s[74:75]
	v_cndmask_b32_e64 v139, v139, v230, s[76:77]
	v_cndmask_b32_e64 v140, v140, v230, s[78:79]
	v_cndmask_b32_e64 v141, v141, v230, s[80:81]
	v_cmp_gt_i32_e64 s[74:75], 48, v233
	v_cmp_gt_i32_e64 s[76:77], 49, v233
	v_cmp_gt_i32_e64 s[78:79], 50, v233
	v_cmp_gt_i32_e64 s[80:81], 51, v233
	v_cndmask_b32_e64 v142, v142, v230, s[74:75]
	v_cndmask_b32_e64 v143, v143, v230, s[76:77]
	v_cndmask_b32_e64 v144, v144, v230, s[78:79]
	v_cndmask_b32_e64 v145, v145, v230, s[80:81]
	v_cmp_gt_i32_e64 s[74:75], -16, v233
	v_cmp_gt_i32_e64 s[76:77], -15, v233
	v_cmp_gt_i32_e64 s[78:79], -14, v233
	v_cmp_gt_i32_e64 s[80:81], -13, v233
	v_cndmask_b32_e64 v146, v146, v230, s[74:75]
	v_cndmask_b32_e64 v147, v147, v230, s[76:77]
	v_cndmask_b32_e64 v148, v148, v230, s[78:79]
	v_cndmask_b32_e64 v149, v149, v230, s[80:81]
	v_cmp_gt_i32_e64 s[74:75], 0, v233
	v_cmp_gt_i32_e64 s[76:77], 1, v233
	v_cmp_gt_i32_e64 s[78:79], 2, v233
	v_cmp_gt_i32_e64 s[80:81], 3, v233
	v_cndmask_b32_e64 v150, v150, v230, s[74:75]
	v_cndmask_b32_e64 v151, v151, v230, s[76:77]
	v_cndmask_b32_e64 v152, v152, v230, s[78:79]
	v_cndmask_b32_e64 v153, v153, v230, s[80:81]
	v_cmp_gt_i32_e64 s[74:75], 16, v233
	v_cmp_gt_i32_e64 s[76:77], 17, v233
	v_cmp_gt_i32_e64 s[78:79], 18, v233
	v_cmp_gt_i32_e64 s[80:81], 19, v233
	v_cndmask_b32_e64 v154, v154, v230, s[74:75]
	v_cndmask_b32_e64 v155, v155, v230, s[76:77]
	v_cndmask_b32_e64 v156, v156, v230, s[78:79]
	v_cndmask_b32_e64 v157, v157, v230, s[80:81]
	v_cmp_gt_i32_e64 s[74:75], 32, v233
	v_cmp_gt_i32_e64 s[76:77], 33, v233
	v_cmp_gt_i32_e64 s[78:79], 34, v233
	v_cmp_gt_i32_e64 s[80:81], 35, v233
	v_cndmask_b32_e64 v158, v158, v230, s[74:75]
	v_cndmask_b32_e64 v159, v159, v230, s[76:77]
	v_cndmask_b32_e64 v160, v160, v230, s[78:79]
	v_cndmask_b32_e64 v161, v161, v230, s[80:81]

.Ld16c_end0:
	s_waitcnt vmcnt(0)
	s_cmp_gt_u32 s61, s59
	s_cselect_b64 s[40:41], -1, 0
	s_and_b64 vcc, exec, s[40:41]
	s_waitcnt vmcnt(0) lgkmcnt(0)
	s_barrier
	ds_read_b128 v[238:241], v218 offset:16384
	ds_read_b128 v[242:245], v219 offset:16384
	ds_read_b128 v[246:249], v218 offset:16512
	s_cbranch_vccnz .LBB0_2418
	s_mov_b64 s[42:43], src_shared_base
	s_cmp_lg_u32 0, -1
	s_cselect_b32 s42, 0, 0
	s_cselect_b32 s43, s43, 0
	s_add_u32 s42, s42, 0x10000
	s_addc_u32 s43, s43, 0
	s_cmp_lg_u64 s[42:43], 0
	s_cselect_b32 s42, s42, -1
	s_add_i32 s42, s42, s57
	v_lshl_add_u64 v[130:131], v[206:207], 0, s[24:25]
	s_mov_b32 m0, s42
	s_nop 0
	global_load_lds_dwordx4 v[130:131], off
	v_lshl_add_u64 v[130:131], v[204:205], 0, s[24:25]
	s_add_i32 m0, s42, 0x400
	s_add_i32 s42, s58, 0
	global_load_lds_dwordx4 v[130:131], off
	v_lshl_add_u64 v[130:131], v[202:203], 0, s[26:27]
	s_mov_b32 m0, s42
	s_nop 0
	global_load_lds_dwordx4 v[130:131], off
	v_lshl_add_u64 v[130:131], v[202:203], 0, s[28:29]
	s_add_i32 m0, s42, 0x400
	s_nop 0
	global_load_lds_dwordx4 v[130:131], off
	v_lshl_add_u64 v[130:131], v[202:203], 0, s[30:31]
	s_add_i32 m0, s42, 0x800
	s_nop 0
	global_load_lds_dwordx4 v[130:131], off
	v_lshl_add_u64 v[130:131], v[202:203], 0, s[34:35]
	s_add_i32 m0, s42, 0xc00
	s_nop 0
	global_load_lds_dwordx4 v[130:131], off
.LBB0_2418:
	s_sub_i32 s73, s60, 94
	s_cmp_gt_i32 s73, s4
	s_cbranch_scc1 .Ld16c_end1
	ds_read_b128 v[252:255], v219 offset:16512
	s_waitcnt lgkmcnt(3)
	v_mfma_f32_16x16x32_bf16 v[130:133], v[238:241], v[162:165], 0
	v_mfma_f32_16x16x32_bf16 v[146:149], v[238:241], v[178:181], 0
	ds_read_b128 v[238:241], v218 offset:20480
	s_waitcnt lgkmcnt(3)
	v_mfma_f32_16x16x32_bf16 v[130:133], v[242:245], v[166:169], v[130:133]
	v_mfma_f32_16x16x32_bf16 v[146:149], v[242:245], v[182:185], v[146:149]
	ds_read_b128 v[242:245], v219 offset:20480
	s_waitcnt lgkmcnt(3)
	v_mfma_f32_16x16x32_bf16 v[130:133], v[246:249], v[170:173], v[130:133]
	v_mfma_f32_16x16x32_bf16 v[146:149], v[246:249], v[186:189], v[146:149]
	ds_read_b128 v[246:249], v218 offset:20608
	s_waitcnt lgkmcnt(3)
	v_mfma_f32_16x16x32_bf16 v[130:133], v[252:255], v[174:177], v[130:133]
	v_mfma_f32_16x16x32_bf16 v[146:149], v[252:255], v[190:193], v[146:149]
	ds_read_b128 v[252:255], v219 offset:20608
	s_waitcnt lgkmcnt(3)
	v_mfma_f32_16x16x32_bf16 v[134:137], v[238:241], v[162:165], 0
	v_mfma_f32_16x16x32_bf16 v[150:153], v[238:241], v[178:181], 0
	ds_read_b128 v[238:241], v218 offset:24576
	s_waitcnt lgkmcnt(3)
	v_mfma_f32_16x16x32_bf16 v[134:137], v[242:245], v[166:169], v[134:137]
	v_mfma_f32_16x16x32_bf16 v[150:153], v[242:245], v[182:185], v[150:153]
	ds_read_b128 v[242:245], v219 offset:24576
	s_waitcnt lgkmcnt(3)
	v_mfma_f32_16x16x32_bf16 v[134:137], v[246:249], v[170:173], v[134:137]
	v_mfma_f32_16x16x32_bf16 v[150:153], v[246:249], v[186:189], v[150:153]
	ds_read_b128 v[246:249], v218 offset:24704
	s_waitcnt lgkmcnt(3)
	v_mfma_f32_16x16x32_bf16 v[134:137], v[252:255], v[174:177], v[134:137]
	v_mfma_f32_16x16x32_bf16 v[150:153], v[252:255], v[190:193], v[150:153]
	ds_read_b128 v[252:255], v219 offset:24704
	s_waitcnt lgkmcnt(3)
	v_mfma_f32_16x16x32_bf16 v[138:141], v[238:241], v[162:165], 0
	v_mfma_f32_16x16x32_bf16 v[154:157], v[238:241], v[178:181], 0
	ds_read_b128 v[238:241], v218 offset:28672
	s_waitcnt lgkmcnt(3)
	v_mfma_f32_16x16x32_bf16 v[138:141], v[242:245], v[166:169], v[138:141]
	v_mfma_f32_16x16x32_bf16 v[154:157], v[242:245], v[182:185], v[154:157]
	ds_read_b128 v[242:245], v219 offset:28672
	s_waitcnt lgkmcnt(3)
	v_mfma_f32_16x16x32_bf16 v[138:141], v[246:249], v[170:173], v[138:141]
	v_mfma_f32_16x16x32_bf16 v[154:157], v[246:249], v[186:189], v[154:157]
	ds_read_b128 v[246:249], v218 offset:28800
	s_waitcnt lgkmcnt(3)
	v_mfma_f32_16x16x32_bf16 v[138:141], v[252:255], v[174:177], v[138:141]
	v_mfma_f32_16x16x32_bf16 v[154:157], v[252:255], v[190:193], v[154:157]
	ds_read_b128 v[252:255], v219 offset:28800
	s_waitcnt lgkmcnt(3)
	v_mfma_f32_16x16x32_bf16 v[142:145], v[238:241], v[162:165], 0
	v_mfma_f32_16x16x32_bf16 v[158:161], v[238:241], v[178:181], 0
	s_waitcnt lgkmcnt(2)
	v_mfma_f32_16x16x32_bf16 v[142:145], v[242:245], v[166:169], v[142:145]
	v_mfma_f32_16x16x32_bf16 v[158:161], v[242:245], v[182:185], v[158:161]
	s_waitcnt lgkmcnt(1)
	v_mfma_f32_16x16x32_bf16 v[142:145], v[246:249], v[170:173], v[142:145]
	v_mfma_f32_16x16x32_bf16 v[158:161], v[246:249], v[186:189], v[158:161]
	s_waitcnt lgkmcnt(0)
	v_mfma_f32_16x16x32_bf16 v[142:145], v[252:255], v[174:177], v[142:145]
	v_mfma_f32_16x16x32_bf16 v[158:161], v[252:255], v[190:193], v[158:161]
	s_nop 7
	s_nop 1
	s_cmp_le_i32 s60, s4
	s_cbranch_scc1 .Ld16c_nm1
	v_subrev_u32_e32 v246, 64, v233
	v_cmp_gt_i32_e64 s[74:75], 0, v246
	v_cmp_gt_i32_e64 s[76:77], 1, v246
	v_cmp_gt_i32_e64 s[78:79], 2, v246
	v_cmp_gt_i32_e64 s[80:81], 3, v246
	v_cndmask_b32_e64 v130, v130, v230, s[74:75]
	v_cndmask_b32_e64 v131, v131, v230, s[76:77]
	v_cndmask_b32_e64 v132, v132, v230, s[78:79]
	v_cndmask_b32_e64 v133, v133, v230, s[80:81]
	v_cmp_gt_i32_e64 s[74:75], 16, v246
	v_cmp_gt_i32_e64 s[76:77], 17, v246
	v_cmp_gt_i32_e64 s[78:79], 18, v246
	v_cmp_gt_i32_e64 s[80:81], 19, v246
	v_cndmask_b32_e64 v134, v134, v230, s[74:75]
	v_cndmask_b32_e64 v135, v135, v230, s[76:77]
	v_cndmask_b32_e64 v136, v136, v230, s[78:79]
	v_cndmask_b32_e64 v137, v137, v230, s[80:81]
	v_cmp_gt_i32_e64 s[74:75], 32, v246
	v_cmp_gt_i32_e64 s[76:77], 33, v246
	v_cmp_gt_i32_e64 s[78:79], 34, v246
	v_cmp_gt_i32_e64 s[80:81], 35, v246
	v_cndmask_b32_e64 v138, v138, v230, s[74:75]
	v_cndmask_b32_e64 v139, v139, v230, s[76:77]
	v_cndmask_b32_e64 v140, v140, v230, s[78:79]
	v_cndmask_b32_e64 v141, v141, v230, s[80:81]
	v_cmp_gt_i32_e64 s[74:75], 48, v246
	v_cmp_gt_i32_e64 s[76:77], 49, v246
	v_cmp_gt_i32_e64 s[78:79], 50, v246
	v_cmp_gt_i32_e64 s[80:81], 51, v246
	v_cndmask_b32_e64 v142, v142, v230, s[74:75]
	v_cndmask_b32_e64 v143, v143, v230, s[76:77]
	v_cndmask_b32_e64 v144, v144, v230, s[78:79]
	v_cndmask_b32_e64 v145, v145, v230, s[80:81]
	v_cmp_gt_i32_e64 s[74:75], -16, v246
	v_cmp_gt_i32_e64 s[76:77], -15, v246
	v_cmp_gt_i32_e64 s[78:79], -14, v246
	v_cmp_gt_i32_e64 s[80:81], -13, v246
	v_cndmask_b32_e64 v146, v146, v230, s[74:75]
	v_cndmask_b32_e64 v147, v147, v230, s[76:77]
	v_cndmask_b32_e64 v148, v148, v230, s[78:79]
	v_cndmask_b32_e64 v149, v149, v230, s[80:81]
	v_cmp_gt_i32_e64 s[74:75], 0, v246
	v_cmp_gt_i32_e64 s[76:77], 1, v246
	v_cmp_gt_i32_e64 s[78:79], 2, v246
	v_cmp_gt_i32_e64 s[80:81], 3, v246
	v_cndmask_b32_e64 v150, v150, v230, s[74:75]
	v_cndmask_b32_e64 v151, v151, v230, s[76:77]
	v_cndmask_b32_e64 v152, v152, v230, s[78:79]
	v_cndmask_b32_e64 v153, v153, v230, s[80:81]
	v_cmp_gt_i32_e64 s[74:75], 16, v246
	v_cmp_gt_i32_e64 s[76:77], 17, v246
	v_cmp_gt_i32_e64 s[78:79], 18, v246
	v_cmp_gt_i32_e64 s[80:81], 19, v246
	v_cndmask_b32_e64 v154, v154, v230, s[74:75]
	v_cndmask_b32_e64 v155, v155, v230, s[76:77]
	v_cndmask_b32_e64 v156, v156, v230, s[78:79]
	v_cndmask_b32_e64 v157, v157, v230, s[80:81]
	v_cmp_gt_i32_e64 s[74:75], 32, v246
	v_cmp_gt_i32_e64 s[76:77], 33, v246
	v_cmp_gt_i32_e64 s[78:79], 34, v246
	v_cmp_gt_i32_e64 s[80:81], 35, v246
	v_cndmask_b32_e64 v158, v158, v230, s[74:75]
	v_cndmask_b32_e64 v159, v159, v230, s[76:77]
	v_cndmask_b32_e64 v160, v160, v230, s[78:79]
	v_cndmask_b32_e64 v161, v161, v230, s[80:81]
